# first norm loop (phase 0): mid-row waits no longer wait on the next row's prefetch; one counted wait before the register rotation
# baseline (speedup 1.0000x reference)
; __device__ __forceinline__ void norm_phase(const float* lat, const float* ctxp, const bf16_t* dbuf, const bf16_t* dbuf2, const bf16_t* dpart, float* xout, int nrows, const float* gw, const float* mod, int shift_off, int scale_off, bf16_t* outb, float* outf) {
;     const int wid = threadIdx.x >> 6, lane = threadIdx.x & 63;
;     const int nw = gridDim.x * 8, gwv = blockIdx.x * 8 + wid, per = (nrows + nw - 1) / nw;
;     const int rb = gwv * per, re = (rb + per < nrows) ? rb + per : nrows;
;     if (rb >= re) return;
;     int cur_b = -1;
;     f32x4 ca[8], cb[8], v[8]; u32x2 dv[8], dw[8];
;     { const float* src = rb < ML ? lat + (size_t)rb * D : ctxp + (size_t)(rb - ML) * D;
; #pragma unroll
;       for (int i = 0; i < 8; ++i) { v[i] = __builtin_nontemporal_load((const f32x4*)(src + i * 256 + lane * 4)); dv[i] = (u32x2){0u, 0u}; if (dbuf && !dpart) dv[i] = *(const u32x2*)(dbuf + (size_t)rb * D + i * 256 + lane * 4);
;           dw[i] = (u32x2){0u, 0u}; if (dbuf2) dw[i] = __builtin_nontemporal_load((const u32x2*)(dbuf2 + (size_t)rb * D + i * 256 + lane * 4)); } }
.LBB0_89:
	s_or_b64 exec, exec, s[0:1]
	s_lshl_b32 s0, s78, 3
	s_abs_i32 s1, s0
	v_cvt_f32_u32_e32 v0, s1
	s_add_i32 s3, s0, 0x87ff
	s_xor_b32 s4, s3, s0
	s_sub_i32 s0, 0xffff7801, s0
	v_rcp_iflag_f32_e32 v0, v0
	s_max_i32 s0, s3, s0
	s_sub_i32 s3, 0, s1
	s_ashr_i32 s4, s4, 31
	v_mul_f32_e32 v0, 0x4f7ffffe, v0
	v_cvt_u32_f32_e32 v0, v0
	v_lshrrev_b32_e32 v1, 6, v140
	v_lshl_add_u32 v1, s2, 3, v1
	v_readfirstlane_b32 s5, v0
	s_mul_i32 s3, s3, s5
	s_mul_hi_u32 s3, s5, s3
	s_add_i32 s5, s5, s3
	s_mul_hi_u32 s3, s0, s5
	s_mul_i32 s5, s3, s1
	s_sub_i32 s0, s0, s5
	s_add_i32 s5, s3, 1
	s_sub_i32 s6, s0, s1
	s_cmp_ge_u32 s0, s1
	s_cselect_b32 s3, s5, s3
	s_cselect_b32 s0, s6, s0
	s_add_i32 s5, s3, 1
	s_cmp_ge_u32 s0, s1
	s_cselect_b32 s0, s5, s3
	s_xor_b32 s0, s0, s4
	s_sub_i32 s0, s0, s4
	v_mul_lo_u32 v160, s0, v1
	v_add_u32_e32 v0, s0, v160
	v_min_i32_e32 v131, 0x8800, v0
	v_cmp_lt_i32_e32 vcc, v160, v131
	s_barrier
	s_and_saveexec_b64 s[4:5], vcc
	s_cbranch_execz .LBB0_96
	s_mov_b32 s0, 0x8000
	v_add_u32_e32 v0, 0xffff8000, v160
	v_ashrrev_i32_e32 v161, 31, v160
	v_cmp_gt_i32_e32 vcc, s0, v160
	v_mov_b32_e32 v2, s41
	v_mov_b32_e32 v3, s37
	v_cndmask_b32_e32 v1, 0, v161, vcc
	v_cndmask_b32_e32 v0, v0, v160, vcc
	v_cndmask_b32_e32 v3, v2, v3, vcc
	v_mov_b32_e32 v2, s40
	v_mov_b32_e32 v4, s36
	v_cndmask_b32_e32 v2, v2, v4, vcc
	v_lshlrev_b64 v[0:1], 13, v[0:1]
	v_lshl_add_u64 v[0:1], v[2:3], 0, v[0:1]
	v_lshlrev_b32_e32 v2, 2, v140
	v_and_b32_e32 v130, 0xfc, v2
	v_mov_b32_e32 v129, 0
	v_lshlrev_b32_e32 v128, 2, v130
	v_lshl_add_u64 v[0:1], v[0:1], 0, v[128:129]
	s_movk_i32 s3, 0x1000
	global_load_dwordx4 v[32:35], v[0:1], off nt
	global_load_dwordx4 v[28:31], v[0:1], off offset:1024 nt
	global_load_dwordx4 v[24:27], v[0:1], off offset:2048 nt
	global_load_dwordx4 v[12:15], v[0:1], off offset:3072 nt
	v_add_co_u32_e32 v0, vcc, s3, v0
	v_or_b32_e32 v38, 0x400, v130
	s_nop 0
	v_addc_co_u32_e32 v1, vcc, 0, v1, vcc
	global_load_dwordx4 v[20:23], v[0:1], off nt
	global_load_dwordx4 v[16:19], v[0:1], off offset:1024 nt
	global_load_dwordx4 v[8:11], v[0:1], off offset:2048 nt
	global_load_dwordx4 v[4:7], v[0:1], off offset:3072 nt
	v_mbcnt_lo_u32_b32 v1, -1, 0
	v_mbcnt_hi_u32_b32 v1, -1, v1
	v_and_b32_e32 v3, 64, v1
	v_add_u32_e32 v3, 64, v3
	v_xor_b32_e32 v37, 32, v1
	v_cmp_lt_i32_e32 vcc, v37, v3
	v_lshl_add_u64 v[132:133], s[48:49], 0, v[128:129]
	v_lshlrev_b32_e32 v128, 2, v38
	v_cndmask_b32_e32 v37, v1, v37, vcc
	v_lshlrev_b32_e32 v141, 2, v37
	v_xor_b32_e32 v37, 16, v1
	v_cmp_lt_i32_e32 vcc, v37, v3
	v_or_b32_e32 v40, 0x500, v130
	v_lshl_add_u64 v[134:135], s[48:49], 0, v[128:129]
	v_cndmask_b32_e32 v37, v1, v37, vcc
	v_lshlrev_b32_e32 v164, 2, v37
	v_xor_b32_e32 v37, 8, v1
	v_cmp_lt_i32_e32 vcc, v37, v3
	v_lshlrev_b32_e32 v128, 2, v40
	v_or_b32_e32 v42, 0x600, v130
	v_cndmask_b32_e32 v37, v1, v37, vcc
	v_lshlrev_b32_e32 v165, 2, v37
	v_xor_b32_e32 v37, 4, v1
	v_cmp_lt_i32_e32 vcc, v37, v3
	v_lshlrev_b64 v[46:47], 12, v[160:161]
	v_lshl_add_u64 v[136:137], s[48:49], 0, v[128:129]
	v_cndmask_b32_e32 v37, v1, v37, vcc
	v_lshlrev_b32_e32 v166, 2, v37
	v_xor_b32_e32 v37, 2, v1
	v_cmp_lt_i32_e32 vcc, v37, v3
	v_lshlrev_b32_e32 v128, 2, v42
	v_or_b32_e32 v44, 0x700, v130
	v_cndmask_b32_e32 v37, v1, v37, vcc
	v_lshlrev_b32_e32 v167, 2, v37
	v_xor_b32_e32 v37, 1, v1
	v_cmp_lt_i32_e32 vcc, v37, v3
	s_add_u32 s6, s74, 0xa100000
	v_or_b32_e32 v0, 0x100, v130
	v_cndmask_b32_e32 v1, v1, v37, vcc
	v_lshlrev_b32_e32 v168, 2, v1
	v_and_b32_e32 v1, 63, v140
	v_lshl_or_b32 v46, v1, 3, v46
	v_or_b32_e32 v2, 0x200, v130
	v_or_b32_e32 v36, 0x300, v130
	v_lshl_add_u64 v[138:139], s[48:49], 0, v[128:129]
	v_lshlrev_b32_e32 v128, 2, v44
	v_lshl_add_u64 v[46:47], s[74:75], 0, v[46:47]
	s_mov_b64 s[0:1], 0xa1a2000
	s_addc_u32 s7, s75, 0
	v_lshl_add_u64 v[142:143], s[48:49], 0, v[128:129]
	v_mov_b32_e32 v147, -1
	v_lshl_add_u64 v[144:145], v[46:47], 0, s[0:1]
	s_mov_b64 s[8:9], 0
	s_mov_b64 s[12:13], 0x2000
	v_lshlrev_b32_e32 v146, 2, v0
	v_lshlrev_b32_e32 v148, 2, v2
	v_lshlrev_b32_e32 v150, 2, v36
	v_lshlrev_b32_e32 v152, 2, v38
	v_lshlrev_b32_e32 v154, 2, v40
	v_lshlrev_b32_e32 v156, 2, v42
	v_lshlrev_b32_e32 v158, 2, v44
	s_movk_i32 s10, 0x7fff
	v_mov_b32_e32 v169, 0x358637bd
	s_mov_b32 s11, 0x800000
	s_mov_b64 s[24:25], 0x1000
	s_waitcnt vmcnt(0)
	s_branch .LBB0_92
; __device__ __forceinline__ unsigned cvt_pk_bf16(float lo, float hi) { unsigned r; asm volatile("v_cvt_pk_bf16_f32 %0, %1, %2" : "=v"(r) : "v"(lo), "v"(hi)); return r; }
; __device__ __forceinline__ float bflo(unsigned u) { return __uint_as_float(u << 16); }
; __device__ __forceinline__ float bfhi(unsigned u) { return __uint_as_float(u & 0xffff0000u); }
; __device__ __forceinline__ void norm_phase(const float* lat, const float* ctxp, const bf16_t* dbuf, const bf16_t* dbuf2, const bf16_t* dpart, float* xout, int nrows, const float* gw, const float* mod, int shift_off, int scale_off, bf16_t* outb, float* outf) {
;     ...
;         float ss = 0.f;
; #pragma unroll
;         for (int i = 0; i < 8; ++i) {
;             v[i][0] += bflo(dv[i].x) + bflo(dw[i].x); v[i][1] += bfhi(dv[i].x) + bfhi(dw[i].x); v[i][2] += bflo(dv[i].y) + bflo(dw[i].y); v[i][3] += bfhi(dv[i].y) + bfhi(dw[i].y);
;             ss += v[i][0] * v[i][0] + v[i][1] * v[i][1] + v[i][2] * v[i][2] + v[i][3] * v[i][3]; }
;         ss = wave_sum(ss);
;         const float rstd = rsqrtf(ss * (1.f / 2048.f) + 1e-6f);
; #pragma unroll
;         for (int i = 0; i < 8; ++i) {
;             const int col = i * 256 + lane * 4;
;             if (xout && row < ML) __builtin_nontemporal_store(v[i], (f32x4*)(xout + (size_t)row * D + col));
;             const f32x4 y = v[i] * rstd * ca[i] + cb[i];
;             if (outb) { u32x2 o; o.x = cvt_pk_bf16(y[0], y[1]); o.y = cvt_pk_bf16(y[2], y[3]); *(u32x2*)(outb + (size_t)row * D + col) = o; }
;             else __builtin_nontemporal_store(y, (f32x4*)(outf + (size_t)row * D + col));
;         }
.LBB0_91:
	s_or_b64 exec, exec, s[26:27]
	v_pk_add_f32 v[20:21], v[20:21], 0 op_sel_hi:[1,0]
	v_pk_add_f32 v[16:17], v[16:17], 0 op_sel_hi:[1,0]
	v_pk_add_f32 v[32:33], v[32:33], 0 op_sel_hi:[1,0]
	v_pk_add_f32 v[28:29], v[28:29], 0 op_sel_hi:[1,0]
	v_mov_b32_e32 v182, v17
	v_mov_b32_e32 v183, v21
	v_pk_add_f32 v[34:35], v[34:35], 0 op_sel_hi:[1,0]
	v_pk_mul_f32 v[160:161], v[32:33], v[32:33]
	v_pk_add_f32 v[30:31], v[30:31], 0 op_sel_hi:[1,0]
	v_pk_mul_f32 v[172:173], v[28:29], v[28:29]
	v_pk_add_f32 v[22:23], v[22:23], 0 op_sel_hi:[1,0]
	v_pk_add_f32 v[18:19], v[18:19], 0 op_sel_hi:[1,0]
	v_mov_b32_e32 v180, v16
	v_mov_b32_e32 v181, v20
	v_pk_mul_f32 v[182:183], v[182:183], v[182:183]
	v_pk_mul_f32 v[170:171], v[34:35], v[34:35]
	v_pk_mul_f32 v[174:175], v[30:31], v[30:31]
	v_pk_fma_f32 v[180:181], v[180:181], v[180:181], v[182:183]
	v_mov_b32_e32 v182, v18
	v_mov_b32_e32 v183, v22
	v_pk_add_f32 v[8:9], v[8:9], 0 op_sel_hi:[1,0]
	v_pk_add_f32 v[4:5], v[4:5], 0 op_sel_hi:[1,0]
	v_add_f32_e32 v128, v172, v173
	v_add_f32_e32 v149, v160, v161
	v_pk_add_f32 v[24:25], v[24:25], 0 op_sel_hi:[1,0]
	v_pk_fma_f32 v[180:181], v[182:183], v[182:183], v[180:181]
	v_mov_b32_e32 v182, v19
	v_mov_b32_e32 v183, v23
	v_mov_b32_e32 v184, v5
	v_mov_b32_e32 v185, v9
	v_add_f32_e32 v128, v174, v128
	v_add_f32_e32 v149, v170, v149
	v_pk_add_f32 v[26:27], v[26:27], 0 op_sel_hi:[1,0]
	v_pk_mul_f32 v[176:177], v[24:25], v[24:25]
	v_pk_fma_f32 v[180:181], v[182:183], v[182:183], v[180:181]
	v_pk_add_f32 v[10:11], v[10:11], 0 op_sel_hi:[1,0]
	v_pk_add_f32 v[6:7], v[6:7], 0 op_sel_hi:[1,0]
	v_mov_b32_e32 v182, v4
	v_mov_b32_e32 v183, v8
	v_pk_mul_f32 v[184:185], v[184:185], v[184:185]
	v_add_f32_e32 v128, v175, v128
	v_add_f32_e32 v149, v171, v149
	v_pk_mul_f32 v[178:179], v[26:27], v[26:27]
	v_pk_fma_f32 v[182:183], v[182:183], v[182:183], v[184:185]
	v_mov_b32_e32 v184, v6
	v_mov_b32_e32 v185, v10
	v_add_f32_e32 v128, v149, v128
	v_add_f32_e32 v149, v176, v177
	v_pk_add_f32 v[12:13], v[12:13], 0 op_sel_hi:[1,0]
	v_pk_fma_f32 v[182:183], v[184:185], v[184:185], v[182:183]
	v_mov_b32_e32 v184, v7
	v_mov_b32_e32 v185, v11
	v_add_f32_e32 v149, v178, v149
	v_pk_add_f32 v[14:15], v[14:15], 0 op_sel_hi:[1,0]
	v_pk_fma_f32 v[182:183], v[184:185], v[184:185], v[182:183]
	v_pk_mul_f32 v[184:185], v[12:13], v[12:13]
	v_add_f32_e32 v149, v179, v149
	v_pk_mul_f32 v[172:173], v[14:15], v[14:15]
	v_add_f32_e32 v128, v149, v128
	v_add_f32_e32 v149, v184, v185
	v_add_f32_e32 v149, v172, v149
	v_add_f32_e32 v149, v173, v149
	v_add_f32_e32 v128, v149, v128
	v_add_f32_e32 v128, v181, v128
	v_add_f32_e32 v128, v180, v128
	v_add_f32_e32 v128, v183, v128
	v_add_f32_e32 v128, v182, v128
	ds_bpermute_b32 v149, v141, v128
	s_and_b64 s[14:15], exec, vcc
	s_or_b64 s[8:9], s[14:15], s[8:9]
	v_mov_b64_e32 v[160:161], v[162:163]
	s_waitcnt lgkmcnt(0)
	v_add_f32_e32 v128, v128, v149
	ds_bpermute_b32 v149, v164, v128
	s_waitcnt lgkmcnt(0)
	v_add_f32_e32 v128, v128, v149
	ds_bpermute_b32 v149, v165, v128
	s_waitcnt lgkmcnt(0)
	v_add_f32_e32 v128, v128, v149
	ds_bpermute_b32 v149, v166, v128
	s_waitcnt lgkmcnt(0)
	v_add_f32_e32 v128, v128, v149
	ds_bpermute_b32 v149, v167, v128
	s_waitcnt lgkmcnt(0)
	v_add_f32_e32 v128, v128, v149
	ds_bpermute_b32 v149, v168, v128
	s_waitcnt lgkmcnt(0)
	v_add_f32_e32 v128, v128, v149
	v_fmamk_f32 v128, v128, 0x3a000000, v169
	v_mul_f32_e32 v149, 0x4b800000, v128
	v_cmp_gt_f32_e64 s[0:1], s11, v128
	s_nop 1
	v_cndmask_b32_e64 v128, v128, v149, s[0:1]
	v_rsq_f32_e32 v128, v128
	s_nop 0
	v_mul_f32_e32 v149, 0x45800000, v128
	v_cndmask_b32_e64 v128, v128, v149, s[0:1]
	v_pk_mul_f32 v[32:33], v[32:33], v[128:129] op_sel_hi:[1,0]
	v_pk_mul_f32 v[28:29], v[28:29], v[128:129] op_sel_hi:[1,0]
	v_pk_mul_f32 v[24:25], v[24:25], v[128:129] op_sel_hi:[1,0]
	v_pk_mul_f32 v[12:13], v[12:13], v[128:129] op_sel_hi:[1,0]
	v_pk_mul_f32 v[34:35], v[34:35], v[128:129] op_sel_hi:[1,0]
	v_pk_fma_f32 v[32:33], v[64:65], v[32:33], v[0:1]
	v_pk_mul_f32 v[30:31], v[30:31], v[128:129] op_sel_hi:[1,0]
	v_pk_fma_f32 v[28:29], v[68:69], v[28:29], v[40:41]
	v_pk_mul_f32 v[26:27], v[26:27], v[128:129] op_sel_hi:[1,0]
	v_pk_fma_f32 v[24:25], v[72:73], v[24:25], v[36:37]
	v_pk_mul_f32 v[14:15], v[14:15], v[128:129] op_sel_hi:[1,0]
	v_pk_fma_f32 v[12:13], v[76:77], v[12:13], v[44:45]
	v_pk_fma_f32 v[34:35], v[66:67], v[34:35], v[2:3]
	v_cvt_pk_bf16_f32 v32, v32, v33
	v_pk_fma_f32 v[30:31], v[70:71], v[30:31], v[42:43]
	v_cvt_pk_bf16_f32 v33, v34, v35
	global_store_dwordx2 v[144:145], v[32:33], off
	v_cvt_pk_bf16_f32 v28, v28, v29
	v_cvt_pk_bf16_f32 v29, v30, v31
	global_store_dwordx2 v[144:145], v[28:29], off offset:512
	v_pk_fma_f32 v[26:27], v[74:75], v[26:27], v[38:39]
	v_cvt_pk_bf16_f32 v24, v24, v25
	v_pk_fma_f32 v[14:15], v[78:79], v[14:15], v[46:47]
	v_cvt_pk_bf16_f32 v25, v26, v27
	global_store_dwordx2 v[144:145], v[24:25], off offset:1024
	v_cvt_pk_bf16_f32 v12, v12, v13
	v_cvt_pk_bf16_f32 v13, v14, v15
	global_store_dwordx2 v[144:145], v[12:13], off offset:1536
	v_pk_mul_f32 v[12:13], v[20:21], v[128:129] op_sel_hi:[1,0]
	v_pk_mul_f32 v[14:15], v[22:23], v[128:129] op_sel_hi:[1,0]
	v_pk_fma_f32 v[12:13], v[80:81], v[12:13], v[48:49]
	v_pk_fma_f32 v[14:15], v[82:83], v[14:15], v[50:51]
	v_cvt_pk_bf16_f32 v12, v12, v13
	v_pk_mul_f32 v[8:9], v[8:9], v[128:129] op_sel_hi:[1,0]
	v_cvt_pk_bf16_f32 v13, v14, v15
	global_store_dwordx2 v[144:145], v[12:13], off offset:2048
	v_pk_mul_f32 v[12:13], v[16:17], v[128:129] op_sel_hi:[1,0]
	v_pk_mul_f32 v[4:5], v[4:5], v[128:129] op_sel_hi:[1,0]
	v_pk_mul_f32 v[14:15], v[18:19], v[128:129] op_sel_hi:[1,0]
	v_pk_fma_f32 v[12:13], v[84:85], v[12:13], v[52:53]
	v_pk_mul_f32 v[10:11], v[10:11], v[128:129] op_sel_hi:[1,0]
	v_pk_fma_f32 v[8:9], v[88:89], v[8:9], v[56:57]
	v_pk_mul_f32 v[6:7], v[6:7], v[128:129] op_sel_hi:[1,0]
	v_pk_fma_f32 v[4:5], v[92:93], v[4:5], v[60:61]
	v_pk_fma_f32 v[14:15], v[86:87], v[14:15], v[54:55]
	v_cvt_pk_bf16_f32 v12, v12, v13
	v_pk_fma_f32 v[10:11], v[90:91], v[10:11], v[58:59]
	v_cvt_pk_bf16_f32 v13, v14, v15
	global_store_dwordx2 v[144:145], v[12:13], off offset:2560
	v_cvt_pk_bf16_f32 v8, v8, v9
	v_cvt_pk_bf16_f32 v9, v10, v11
	global_store_dwordx2 v[144:145], v[8:9], off offset:3072
	v_pk_fma_f32 v[6:7], v[94:95], v[6:7], v[62:63]
	v_cvt_pk_bf16_f32 v4, v4, v5
	s_waitcnt vmcnt(7)
; __device__ __forceinline__ void norm_phase(const float* lat, const float* ctxp, const bf16_t* dbuf, const bf16_t* dbuf2, const bf16_t* dpart, float* xout, int nrows, const float* gw, const float* mod, int shift_off, int scale_off, bf16_t* outb, float* outf) {
;     ...
;     for (int row = rb; row < re; ++row) {
;         const int b = row < ML ? (row >> 12) : 8;
;         if (b != cur_b) {
;             cur_b = b;
; #pragma unroll
;             for (int i = 0; i < 8; ++i) { const int col = i * 256 + lane * 4; ca[i] = *(const f32x4*)(gw + col); cb[i] = (f32x4){0.f, 0.f, 0.f, 0.f};
;                 if (mod) { const f32x4 sc = *(const f32x4*)(mod + (size_t)b * NMODC + scale_off + col); cb[i] = *(const f32x4*)(mod + (size_t)b * NMODC + shift_off + col); ca[i] = ca[i] * (sc + 1.f); } }
;         }
;     ...
;         for (int i = 0; i < 8; ++i) { v[i] = nv[i]; dv[i] = nd[i]; dw[i] = nw2[i]; }
	v_mov_b32_e32 v32, v124
	v_cvt_pk_bf16_f32 v5, v6, v7
	global_store_dwordx2 v[144:145], v[4:5], off offset:3584
	v_lshl_add_u64 v[144:145], v[144:145], 0, s[24:25]
	v_mov_b32_e32 v33, v125
	v_mov_b32_e32 v34, v126
	v_mov_b32_e32 v35, v127
	v_mov_b32_e32 v28, v120
	v_mov_b32_e32 v29, v121
	v_mov_b32_e32 v30, v122
	v_mov_b32_e32 v31, v123
	v_mov_b32_e32 v24, v116
	v_mov_b32_e32 v25, v117
	v_mov_b32_e32 v26, v118
	v_mov_b32_e32 v27, v119
	v_mov_b32_e32 v12, v112
	v_mov_b32_e32 v13, v113
	v_mov_b32_e32 v14, v114
	v_mov_b32_e32 v15, v115
	v_mov_b32_e32 v20, v108
	v_mov_b32_e32 v21, v109
	v_mov_b32_e32 v22, v110
	v_mov_b32_e32 v23, v111
	v_mov_b32_e32 v16, v104
	v_mov_b32_e32 v17, v105
	v_mov_b32_e32 v18, v106
	v_mov_b32_e32 v19, v107
	v_mov_b32_e32 v8, v100
	v_mov_b32_e32 v9, v101
	v_mov_b32_e32 v10, v102
	v_mov_b32_e32 v11, v103
	v_mov_b32_e32 v4, v96
	v_mov_b32_e32 v5, v97
	v_mov_b32_e32 v6, v98
	v_mov_b32_e32 v7, v99
	s_andn2_b64 exec, exec, s[8:9]
	s_cbranch_execz .LBB0_96
.LBB0_92:
	v_min_i32_e32 v96, 0x8000, v160
	v_ashrrev_i32_e32 v96, 12, v96
	v_cmp_ne_u32_e32 vcc, v96, v147
	v_lshlrev_b32_e32 v128, 2, v130
	s_and_saveexec_b64 s[0:1], vcc
	s_cbranch_execz .LBB0_94
	v_mul_hi_i32_i24_e32 v1, 0x12000, v96
	v_mul_i32_i24_e32 v0, 0x12000, v96
	v_lshl_add_u64 v[60:61], s[6:7], 0, v[0:1]
	v_lshl_add_u64 v[36:37], v[60:61], 0, s[12:13]
	v_mov_b32_e32 v147, v129
	v_lshl_add_u64 v[0:1], v[36:37], 0, v[128:129]
	v_lshl_add_u64 v[38:39], v[36:37], 0, v[146:147]
	v_mov_b32_e32 v149, v129
	v_lshl_add_u64 v[44:45], v[60:61], 0, v[128:129]
	global_load_dwordx4 v[64:67], v[0:1], off
	s_nop 0
	global_load_dwordx4 v[0:3], v[44:45], off
	global_load_dwordx4 v[68:71], v[38:39], off
	v_lshl_add_u64 v[38:39], v[36:37], 0, v[148:149]
	v_mov_b32_e32 v151, v129
	v_mov_b32_e32 v153, v129
	v_lshl_add_u64 v[40:41], v[36:37], 0, v[150:151]
	global_load_dwordx4 v[72:75], v[38:39], off
	global_load_dwordx4 v[76:79], v[40:41], off
	v_lshl_add_u64 v[38:39], v[36:37], 0, v[152:153]
	v_mov_b32_e32 v155, v129
	global_load_dwordx4 v[80:83], v[38:39], off
	v_lshl_add_u64 v[38:39], v[36:37], 0, v[154:155]
	v_mov_b32_e32 v157, v129
	global_load_dwordx4 v[84:87], v[38:39], off
	v_lshl_add_u64 v[38:39], v[36:37], 0, v[156:157]
	v_mov_b32_e32 v159, v129
	global_load_dwordx4 v[88:91], v[38:39], off
	v_lshl_add_u64 v[36:37], v[36:37], 0, v[158:159]
	v_lshl_add_u64 v[48:49], v[60:61], 0, v[152:153]
	v_lshl_add_u64 v[52:53], v[60:61], 0, v[154:155]
	global_load_dwordx4 v[92:95], v[36:37], off
	global_load_dwordx4 v[98:101], v[132:133], off
	global_load_dwordx4 v[102:105], v[132:133], off offset:1024
	global_load_dwordx4 v[40:43], v[44:45], off offset:1024
	s_nop 0
	global_load_dwordx4 v[36:39], v[44:45], off offset:2048
	global_load_dwordx4 v[106:109], v[132:133], off offset:2048
	global_load_dwordx4 v[110:113], v[132:133], off offset:3072
	s_nop 0
	global_load_dwordx4 v[44:47], v[44:45], off offset:3072
	s_nop 0
	global_load_dwordx4 v[48:51], v[48:49], off
	s_nop 0
	global_load_dwordx4 v[114:117], v[134:135], off
	global_load_dwordx4 v[118:121], v[136:137], off
	s_nop 0
	global_load_dwordx4 v[52:55], v[52:53], off
	s_nop 0
	global_load_dwordx4 v[122:125], v[138:139], off
	v_lshl_add_u64 v[56:57], v[60:61], 0, v[156:157]
	v_lshl_add_u64 v[60:61], v[60:61], 0, v[158:159]
	global_load_dwordx4 v[170:173], v[142:143], off
	s_nop 0
	global_load_dwordx4 v[56:59], v[56:57], off
	v_mov_b32_e32 v147, v96
	global_load_dwordx4 v[60:63], v[60:61], off
	s_waitcnt vmcnt(23)
	v_pk_add_f32 v[66:67], v[66:67], 1.0 op_sel_hi:[1,0]
	v_pk_add_f32 v[64:65], v[64:65], 1.0 op_sel_hi:[1,0]
	s_waitcnt vmcnt(21)
	v_pk_add_f32 v[70:71], v[70:71], 1.0 op_sel_hi:[1,0]
	v_pk_add_f32 v[68:69], v[68:69], 1.0 op_sel_hi:[1,0]
	s_waitcnt vmcnt(20)
	v_pk_add_f32 v[74:75], v[74:75], 1.0 op_sel_hi:[1,0]
	v_pk_add_f32 v[72:73], v[72:73], 1.0 op_sel_hi:[1,0]
	s_waitcnt vmcnt(19)
	v_pk_add_f32 v[78:79], v[78:79], 1.0 op_sel_hi:[1,0]
	v_pk_add_f32 v[76:77], v[76:77], 1.0 op_sel_hi:[1,0]
	s_waitcnt vmcnt(18)
	v_pk_add_f32 v[82:83], v[82:83], 1.0 op_sel_hi:[1,0]
	v_pk_add_f32 v[80:81], v[80:81], 1.0 op_sel_hi:[1,0]
	s_waitcnt vmcnt(17)
	v_pk_add_f32 v[86:87], v[86:87], 1.0 op_sel_hi:[1,0]
	v_pk_add_f32 v[84:85], v[84:85], 1.0 op_sel_hi:[1,0]
	s_waitcnt vmcnt(15)
	v_pk_add_f32 v[94:95], v[94:95], 1.0 op_sel_hi:[1,0]
	v_pk_add_f32 v[90:91], v[90:91], 1.0 op_sel_hi:[1,0]
	v_pk_add_f32 v[88:89], v[88:89], 1.0 op_sel_hi:[1,0]
	v_pk_add_f32 v[92:93], v[92:93], 1.0 op_sel_hi:[1,0]
	s_waitcnt vmcnt(14)
	v_pk_mul_f32 v[66:67], v[100:101], v[66:67]
	v_pk_mul_f32 v[64:65], v[98:99], v[64:65]
	s_waitcnt vmcnt(13)
	v_pk_mul_f32 v[70:71], v[104:105], v[70:71]
	v_pk_mul_f32 v[68:69], v[102:103], v[68:69]
	s_waitcnt vmcnt(10)
	v_pk_mul_f32 v[74:75], v[108:109], v[74:75]
	v_pk_mul_f32 v[72:73], v[106:107], v[72:73]
	s_waitcnt vmcnt(9)
	v_pk_mul_f32 v[78:79], v[112:113], v[78:79]
	v_pk_mul_f32 v[76:77], v[110:111], v[76:77]
	s_waitcnt vmcnt(6)
	v_pk_mul_f32 v[82:83], v[116:117], v[82:83]
	v_pk_mul_f32 v[80:81], v[114:115], v[80:81]
	s_waitcnt vmcnt(5)
	v_pk_mul_f32 v[86:87], v[120:121], v[86:87]
	v_pk_mul_f32 v[84:85], v[118:119], v[84:85]
	s_waitcnt vmcnt(3)
	v_pk_mul_f32 v[90:91], v[124:125], v[90:91]
	v_pk_mul_f32 v[88:89], v[122:123], v[88:89]
	s_waitcnt vmcnt(2)
	v_pk_mul_f32 v[94:95], v[172:173], v[94:95]
	v_pk_mul_f32 v[92:93], v[170:171], v[92:93]
	s_waitcnt vmcnt(0)
